# v6 + attention L0 PV as back-to-back dependent MFMA pairs followed by 8 exps
# speedup vs baseline: 1.0025x; 1.0025x over previous
.LBB0_615:
	s_mov_b32 s62, s60
	s_mov_b32 s60, s56
	s_mov_b32 s58, s66
	s_mov_b64 s[22:23], s[44:45]
	s_mov_b32 s59, s65
	v_add_u32_e32 v148, s64, v167
	ds_read_b64_tr_b16 v[140:141], v148 offset:32768
	ds_read_b64_tr_b16 v[142:143], v148 offset:33280
	s_add_i32 s14, s63, 0xffffe000
	s_and_b32 s44, s14, 0x6000
	v_add_u32_e32 v96, s44, v164
	s_waitcnt lgkmcnt(2)
	v_mfma_f32_32x32x16_bf16 v[80:95], v[80:83], v[124:127], 0
	v_add_f32_e32 v64, v48, v49
	v_add_f32_e32 v64, v50, v64
	v_add_f32_e32 v64, v51, v64
	v_add_f32_e32 v64, v52, v64
	v_add_f32_e32 v64, v53, v64
	v_cvt_pk_bf16_f32 v108, v48, v49
	v_cvt_pk_bf16_f32 v109, v50, v51
	ds_read_b64_tr_b16 v[48:49], v148 offset:36864
	ds_read_b64_tr_b16 v[50:51], v148 offset:37376
	v_add_f32_e32 v64, v54, v64
	v_add_f32_e32 v64, v55, v64
	v_add_f32_e32 v64, v56, v64
	v_add_f32_e32 v97, v57, v64
	v_cvt_pk_bf16_f32 v110, v52, v53
	v_cvt_pk_bf16_f32 v111, v54, v55
	v_mfma_f32_32x32x16_bf16 v[64:79], v[136:139], v[124:127], 0
	ds_read_b128 v[52:55], v96 offset:4096
	ds_read_b128 v[136:139], v96 offset:4608
	ds_read_b64_tr_b16 v[144:145], v148 offset:33792
	ds_read_b64_tr_b16 v[146:147], v148 offset:34304
	v_mfma_f32_32x32x16_bf16 v[80:95], v[132:135], v[120:123], v[80:95]
	v_add_f32_e32 v97, v58, v97
	v_add_f32_e32 v97, v59, v97
	v_add_f32_e32 v97, v60, v97
	v_add_f32_e32 v97, v61, v97
	v_cvt_pk_bf16_f32 v104, v56, v57
	v_cvt_pk_bf16_f32 v105, v58, v59
	ds_read_b64_tr_b16 v[56:57], v148 offset:37888
	ds_read_b64_tr_b16 v[58:59], v148 offset:38400
	v_add_f32_e32 v97, v62, v97
	v_add_f32_e32 v97, v63, v97
	v_add_f32_e32 v97, v32, v97
	v_add_f32_e32 v97, v33, v97
	v_cvt_pk_bf16_f32 v106, v60, v61
	v_cvt_pk_bf16_f32 v107, v62, v63
	v_mfma_f32_32x32x16_bf16 v[64:79], v[128:131], v[120:123], v[64:79]
	ds_read_b128 v[60:63], v96 offset:6144
	ds_read_b128 v[128:131], v96 offset:6656
	ds_read_b64_tr_b16 v[132:133], v148 offset:34816
	ds_read_b64_tr_b16 v[134:135], v148 offset:35328
	s_waitcnt lgkmcnt(9)
	v_mfma_f32_32x32x16_bf16 v[80:95], v[52:55], v[116:119], v[80:95]
	v_add_f32_e32 v96, v34, v97
	v_add_f32_e32 v96, v35, v96
	v_add_f32_e32 v96, v36, v96
	v_add_f32_e32 v96, v37, v96
	v_cvt_pk_bf16_f32 v100, v32, v33
	v_cvt_pk_bf16_f32 v101, v34, v35
	ds_read_b64_tr_b16 v[32:33], v148 offset:38912
	ds_read_b64_tr_b16 v[34:35], v148 offset:39424
	v_add_f32_e32 v52, v38, v96
	v_add_f32_e32 v52, v39, v52
	v_add_f32_e32 v52, v40, v52
	v_add_f32_e32 v52, v41, v52
	v_cvt_pk_bf16_f32 v102, v36, v37
	v_cvt_pk_bf16_f32 v103, v38, v39
	s_waitcnt lgkmcnt(10)
	v_mfma_f32_32x32x16_bf16 v[64:79], v[136:139], v[116:119], v[64:79]
	ds_read_b64_tr_b16 v[36:37], v148 offset:35840
	ds_read_b64_tr_b16 v[38:39], v148 offset:36352
	s_waitcnt lgkmcnt(7)
	v_mfma_f32_32x32x16_bf16 v[80:95], v[60:63], v[112:115], v[80:95]
	v_add_f32_e32 v52, v42, v52
	v_add_f32_e32 v52, v43, v52
	v_add_f32_e32 v52, v44, v52
	v_add_f32_e32 v52, v45, v52
	v_cvt_pk_bf16_f32 v96, v40, v41
	v_cvt_pk_bf16_f32 v97, v42, v43
	ds_read_b64_tr_b16 v[40:41], v148 offset:39936
	ds_read_b64_tr_b16 v[42:43], v148 offset:40448
	v_add_f32_e32 v52, v46, v52
	v_add_f32_e32 v52, v47, v52
	v_add_f32_e32 v52, 0, v52
	v_cvt_pk_bf16_f32 v98, v44, v45
	v_cvt_pk_bf16_f32 v99, v46, v47
	s_waitcnt lgkmcnt(8)
	v_mfma_f32_32x32x16_bf16 v[64:79], v[128:131], v[112:115], v[64:79]
	s_add_u32 s34, s42, 0xffff8000
	s_addc_u32 s35, s43, -1
	s_add_i32 s64, s63, 0x4000
	s_and_b32 s14, s64, 0x6000
	s_add_i32 s14, s14, s54
	s_mov_b32 m0, s14
	s_nop 0
	global_load_lds_dwordx4 v169, s[34:35]
	s_add_u32 s34, s40, 0xffff8000
	s_addc_u32 s35, s41, -1
	s_add_i32 s14, s62, s55
	s_mov_b32 m0, s14
	s_nop 0
	global_load_lds_dwordx4 v170, s[34:35]
	v_add_f32_e32 v148, v168, v52
	s_waitcnt lgkmcnt(12)
	v_mfma_f32_32x32x16_bf16 v[0:15], v[108:111], v[140:143], v[0:15]
	v_mfma_f32_32x32x16_bf16 v[0:15], v[104:107], v[144:147], v[0:15]
	v_exp_f32_e32 v80, v80
	v_exp_f32_e32 v81, v81
	v_exp_f32_e32 v82, v82
	v_exp_f32_e32 v83, v83
	v_exp_f32_e32 v84, v84
	v_exp_f32_e32 v85, v85
	v_exp_f32_e32 v86, v86
	v_exp_f32_e32 v87, v87
	s_waitcnt lgkmcnt(2)
	v_mfma_f32_32x32x16_bf16 v[0:15], v[100:103], v[132:135], v[0:15]
	v_mfma_f32_32x32x16_bf16 v[0:15], v[96:99], v[36:39], v[0:15]
	v_exp_f32_e32 v88, v88
	v_exp_f32_e32 v89, v89
	v_exp_f32_e32 v90, v90
	v_exp_f32_e32 v91, v91
	v_exp_f32_e32 v92, v92
	v_exp_f32_e32 v93, v93
	v_exp_f32_e32 v94, v94
	v_exp_f32_e32 v95, v95
	v_mfma_f32_32x32x16_bf16 v[16:31], v[108:111], v[48:51], v[16:31]
	v_mfma_f32_32x32x16_bf16 v[16:31], v[104:107], v[56:59], v[16:31]
	s_and_b32 s14, s63, 0x6000
	v_add_u32_e32 v149, s14, v164
	ds_read_b128 v[44:47], v149
	ds_read_b128 v[128:131], v149 offset:512
	ds_read_b128 v[136:139], v149 offset:2048
	ds_read_b128 v[140:143], v149 offset:2560
	v_exp_f32_e32 v64, v64
	v_exp_f32_e32 v65, v65
	v_exp_f32_e32 v66, v66
	v_exp_f32_e32 v67, v67
	v_exp_f32_e32 v68, v68
	v_exp_f32_e32 v69, v69
	v_exp_f32_e32 v70, v70
	v_exp_f32_e32 v71, v71
	s_waitcnt lgkmcnt(4)
	v_mfma_f32_32x32x16_bf16 v[16:31], v[100:103], v[32:35], v[16:31]
	v_mfma_f32_32x32x16_bf16 v[16:31], v[96:99], v[40:43], v[16:31]
	v_exp_f32_e32 v72, v72
	v_exp_f32_e32 v73, v73
	v_exp_f32_e32 v74, v74
	v_exp_f32_e32 v75, v75
	v_exp_f32_e32 v76, v76
	v_exp_f32_e32 v77, v77
	v_exp_f32_e32 v78, v78
	v_exp_f32_e32 v79, v79
	s_waitcnt vmcnt(2) lgkmcnt(0)
	s_barrier
	s_add_i32 s14, s62, 0x2000
	s_cmpk_lg_i32 s62, 0x4000
	s_cselect_b32 s56, s14, 0
	v_add_u32_e32 v150, s60, v167
	ds_read_b64_tr_b16 v[132:133], v150 offset:32768
	ds_read_b64_tr_b16 v[134:135], v150 offset:33280
	s_waitcnt lgkmcnt(5)
	v_mfma_f32_32x32x16_bf16 v[48:63], v[44:47], v[124:127], 0
	v_add_f32_e32 v32, v80, v81
	v_add_f32_e32 v32, v82, v32
	v_add_f32_e32 v32, v83, v32
	v_add_f32_e32 v32, v84, v32
	v_add_f32_e32 v32, v85, v32
	v_cvt_pk_bf16_f32 v108, v80, v81
	v_cvt_pk_bf16_f32 v109, v82, v83
	ds_read_b64_tr_b16 v[80:81], v150 offset:36864
	ds_read_b64_tr_b16 v[82:83], v150 offset:37376
	v_add_f32_e32 v32, v86, v32
	v_add_f32_e32 v32, v87, v32
	v_add_f32_e32 v32, v88, v32
	v_add_f32_e32 v96, v89, v32
	s_waitcnt lgkmcnt(6)
	v_mfma_f32_32x32x16_bf16 v[32:47], v[128:131], v[124:127], 0
	v_cvt_pk_bf16_f32 v110, v84, v85
	v_cvt_pk_bf16_f32 v111, v86, v87
	ds_read_b128 v[84:87], v149 offset:4096
	ds_read_b128 v[128:131], v149 offset:4608
	ds_read_b64_tr_b16 v[144:145], v150 offset:33792
	ds_read_b64_tr_b16 v[146:147], v150 offset:34304
	s_waitcnt lgkmcnt(9)
	v_mfma_f32_32x32x16_bf16 v[48:63], v[136:139], v[120:123], v[48:63]
	v_add_f32_e32 v96, v90, v96
	v_add_f32_e32 v96, v91, v96
	v_add_f32_e32 v96, v92, v96
	v_add_f32_e32 v96, v93, v96
	v_cvt_pk_bf16_f32 v104, v88, v89
	v_cvt_pk_bf16_f32 v105, v90, v91
	ds_read_b64_tr_b16 v[88:89], v150 offset:37888
	ds_read_b64_tr_b16 v[90:91], v150 offset:38400
	s_waitcnt lgkmcnt(10)
	v_mfma_f32_32x32x16_bf16 v[32:47], v[140:143], v[120:123], v[32:47]
	v_add_f32_e32 v96, v94, v96
	v_add_f32_e32 v96, v95, v96
	v_add_f32_e32 v96, v64, v96
	v_add_f32_e32 v96, v65, v96
	v_cvt_pk_bf16_f32 v106, v92, v93
	v_cvt_pk_bf16_f32 v107, v94, v95
	ds_read_b128 v[92:95], v149 offset:6144
	ds_read_b128 v[136:139], v149 offset:6656
	ds_read_b64_tr_b16 v[140:141], v150 offset:34816
	ds_read_b64_tr_b16 v[142:143], v150 offset:35328
	s_waitcnt lgkmcnt(9)
	v_mfma_f32_32x32x16_bf16 v[48:63], v[84:87], v[116:119], v[48:63]
	v_add_f32_e32 v96, v66, v96
	v_add_f32_e32 v96, v67, v96
	v_add_f32_e32 v96, v68, v96
	v_add_f32_e32 v96, v69, v96
	v_cvt_pk_bf16_f32 v100, v64, v65
	v_cvt_pk_bf16_f32 v101, v66, v67
	ds_read_b64_tr_b16 v[64:65], v150 offset:38912
	ds_read_b64_tr_b16 v[66:67], v150 offset:39424
	s_waitcnt lgkmcnt(10)
	v_mfma_f32_32x32x16_bf16 v[32:47], v[128:131], v[116:119], v[32:47]
	v_add_f32_e32 v84, v70, v96
	v_add_f32_e32 v84, v71, v84
	v_add_f32_e32 v84, v72, v84
	v_add_f32_e32 v84, v73, v84
	v_cvt_pk_bf16_f32 v102, v68, v69
	v_cvt_pk_bf16_f32 v103, v70, v71
	ds_read_b64_tr_b16 v[68:69], v150 offset:35840
	ds_read_b64_tr_b16 v[70:71], v150 offset:36352
	s_waitcnt lgkmcnt(7)
	v_mfma_f32_32x32x16_bf16 v[48:63], v[92:95], v[112:115], v[48:63]
	v_add_f32_e32 v84, v74, v84
	v_add_f32_e32 v84, v75, v84
	v_add_f32_e32 v84, v76, v84
	v_add_f32_e32 v84, v77, v84
	v_cvt_pk_bf16_f32 v96, v72, v73
	v_cvt_pk_bf16_f32 v97, v74, v75
	ds_read_b64_tr_b16 v[72:73], v150 offset:39936
	ds_read_b64_tr_b16 v[74:75], v150 offset:40448
	s_waitcnt lgkmcnt(8)
	v_mfma_f32_32x32x16_bf16 v[32:47], v[136:139], v[112:115], v[32:47]
	v_add_f32_e32 v84, v78, v84
	v_add_f32_e32 v84, v79, v84
	v_add_f32_e32 v84, 0, v84
	v_cvt_pk_bf16_f32 v98, v76, v77
	v_cvt_pk_bf16_f32 v99, v78, v79
	s_add_i32 s14, s44, s54
	s_mov_b32 m0, s14
	s_nop 0
	global_load_lds_dwordx4 v169, s[42:43]
	s_add_i32 s14, s56, s55
	s_mov_b32 m0, s14
	s_nop 0
	global_load_lds_dwordx4 v170, s[40:41]
	v_add_f32_e32 v168, v148, v84
	s_add_i32 s57, s57, 2
	s_waitcnt lgkmcnt(12)
	v_mfma_f32_32x32x16_bf16 v[0:15], v[108:111], v[132:135], v[0:15]
	v_mfma_f32_32x32x16_bf16 v[0:15], v[104:107], v[144:147], v[0:15]
	v_exp_f32_e32 v48, v48
	v_exp_f32_e32 v49, v49
	v_exp_f32_e32 v50, v50
	v_exp_f32_e32 v51, v51
	v_exp_f32_e32 v52, v52
	v_exp_f32_e32 v53, v53
	v_exp_f32_e32 v54, v54
	v_exp_f32_e32 v55, v55
	s_waitcnt lgkmcnt(2)
	v_mfma_f32_32x32x16_bf16 v[0:15], v[100:103], v[140:143], v[0:15]
	v_mfma_f32_32x32x16_bf16 v[0:15], v[96:99], v[68:71], v[0:15]
	v_exp_f32_e32 v56, v56
	v_exp_f32_e32 v57, v57
	v_exp_f32_e32 v58, v58
	v_exp_f32_e32 v59, v59
	v_exp_f32_e32 v60, v60
	v_exp_f32_e32 v61, v61
	v_exp_f32_e32 v62, v62
	v_exp_f32_e32 v63, v63
	v_mfma_f32_32x32x16_bf16 v[16:31], v[108:111], v[80:83], v[16:31]
	v_mfma_f32_32x32x16_bf16 v[16:31], v[104:107], v[88:91], v[16:31]
	s_add_i32 s14, s63, 0x2000
	s_and_b32 s14, s14, 0x6000
	v_add_u32_e32 v76, s14, v164
	ds_read_b128 v[80:83], v76
	ds_read_b128 v[136:139], v76 offset:512
	ds_read_b128 v[132:135], v76 offset:2048
	ds_read_b128 v[128:131], v76 offset:2560
	v_exp_f32_e32 v32, v32
	v_exp_f32_e32 v33, v33
	v_exp_f32_e32 v34, v34
	v_exp_f32_e32 v35, v35
	v_exp_f32_e32 v36, v36
	v_exp_f32_e32 v37, v37
	v_exp_f32_e32 v38, v38
	v_exp_f32_e32 v39, v39
	s_waitcnt lgkmcnt(4)
	v_mfma_f32_32x32x16_bf16 v[16:31], v[100:103], v[64:67], v[16:31]
	v_mfma_f32_32x32x16_bf16 v[16:31], v[96:99], v[72:75], v[16:31]
	v_exp_f32_e32 v40, v40
	v_exp_f32_e32 v41, v41
	v_exp_f32_e32 v42, v42
	v_exp_f32_e32 v43, v43
	v_exp_f32_e32 v44, v44
	v_exp_f32_e32 v45, v45
	v_exp_f32_e32 v46, v46
	v_exp_f32_e32 v47, v47
	s_add_i32 s14, s56, 0x2000
	s_cmpk_lg_i32 s56, 0x4000
	s_cselect_b32 s60, s14, 0
	s_add_u32 s40, s40, 0x10000
	s_addc_u32 s41, s41, 0
	s_add_u32 s42, s42, 0x10000
	s_addc_u32 s43, s43, 0
	s_addk_i32 s66, 0x4000
	s_waitcnt vmcnt(2) lgkmcnt(0)
	s_barrier
	s_add_u32 s44, s22, 0x10000
	s_addc_u32 s45, s23, 0
	s_add_i32 s65, s65, 2
	s_cmp_ge_u32 s57, s61
	s_mov_b32 s63, s64
	s_mov_b32 s64, s62
	s_cbranch_scc0 .LBB0_615
	s_add_i32 s14, s57, 1
	s_cmp_ge_u32 s14, s53
	s_cbranch_scc1 .LBB0_644
	s_add_i32 s61, s53, -2
